# attn-B: DMA address SALU hoisted to the start of the softmax segment, DMA issue stays at the tail (on top of v63)
# baseline (speedup 1.0000x reference)
.LBB0_700:
	s_nop 0
	s_add_i32 s100, s18, s28
	s_ashr_i32 s101, s100, 31
	s_lshl_b64 s[100:101], s[100:101], 8
	s_add_u32 s94, s89, s100
	s_addc_u32 s95, s50, s101
	s_add_u32 s100, s78, s100
	s_addc_u32 s101, s88, s101
	s_add_i32 s17, s23, s29
	s_and_b32 s17, s17, 0xc000
	s_add_i32 s29, s17, s91
	s_add_i32 s17, s17, s51
	v_max_f32_e32 v123, v70, v71
	v_max3_f32 v123, v123, v72, v73
	v_max3_f32 v122, v86, v87, v88
	v_max3_f32 v123, v123, v74, v75
	v_max3_f32 v122, v122, v89, v90
	v_max3_f32 v123, v123, v76, v77
	v_max3_f32 v122, v122, v91, v92
	v_max3_f32 v123, v123, v78, v79
	v_max3_f32 v122, v122, v93, v94
	v_max3_f32 v123, v123, v80, v81
	v_max3_f32 v122, v122, v95, v96
	v_max3_f32 v123, v123, v82, v83
	v_cndmask_b32_e32 v5, v167, v166, vcc
	v_max3_f32 v122, v122, v97, v98
	v_max3_f32 v123, v123, v84, v85
	v_max3_f32 v122, v122, v99, v100
	v_add_f32_e32 v123, v5, v123
	v_max3_f32 v122, v122, v101, v123
	v_mov_b32_e32 v123, v122
	s_nop 1
	v_permlane32_swap_b32_e32 v122, v123
	v_mul_f32_e64 v2, v162, |v4|
	v_max_f32_e32 v122, v122, v123
	v_fmac_f32_e32 v2, 0x3e38aa3b, v122
	v_sub_f32_e32 v122, v2, v168
	v_cmp_ge_f32_e32 vcc, s79, v122
	v_max_f32_e32 v2, v168, v2
	s_cmp_eq_u64 vcc, exec
	s_cselect_b64 vcc, -1, 0
	v_sub_f32_e32 v122, v168, v2
	v_cndmask_b32_e32 v168, v2, v168, vcc
	v_fma_f32 v4, v162, |v4|, -v168
	v_fmamk_f32 v86, v86, 0x3e38aa3b, v4
	v_exp_f32_e32 v86, v86
	v_fmamk_f32 v87, v87, 0x3e38aa3b, v4
	v_exp_f32_e32 v87, v87
	v_fmamk_f32 v88, v88, 0x3e38aa3b, v4
	v_exp_f32_e32 v88, v88
	v_fmamk_f32 v89, v89, 0x3e38aa3b, v4
	v_fmamk_f32 v90, v90, 0x3e38aa3b, v4
	v_fmamk_f32 v91, v91, 0x3e38aa3b, v4
	v_fmamk_f32 v92, v92, 0x3e38aa3b, v4
	v_fmamk_f32 v93, v93, 0x3e38aa3b, v4
	v_fmamk_f32 v94, v94, 0x3e38aa3b, v4
	v_fmamk_f32 v95, v95, 0x3e38aa3b, v4
	v_fmamk_f32 v96, v96, 0x3e38aa3b, v4
	v_fmamk_f32 v97, v97, 0x3e38aa3b, v4
	v_fmamk_f32 v98, v98, 0x3e38aa3b, v4
	v_fmamk_f32 v99, v99, 0x3e38aa3b, v4
	v_fmamk_f32 v100, v100, 0x3e38aa3b, v4
	v_fmamk_f32 v101, v101, 0x3e38aa3b, v4
	v_fmac_f32_e32 v4, 0x3e38aa3b, v5
	v_exp_f32_e32 v89, v89
	v_fmamk_f32 v5, v70, 0x3e38aa3b, v4
	v_fmamk_f32 v70, v71, 0x3e38aa3b, v4
	v_fmamk_f32 v71, v72, 0x3e38aa3b, v4
	v_fmamk_f32 v72, v73, 0x3e38aa3b, v4
	v_fmamk_f32 v73, v74, 0x3e38aa3b, v4
	v_fmamk_f32 v74, v75, 0x3e38aa3b, v4
	v_fmamk_f32 v75, v76, 0x3e38aa3b, v4
	v_fmamk_f32 v76, v77, 0x3e38aa3b, v4
	v_fmamk_f32 v77, v78, 0x3e38aa3b, v4
	v_fmamk_f32 v78, v79, 0x3e38aa3b, v4
	v_fmamk_f32 v79, v80, 0x3e38aa3b, v4
	v_fmamk_f32 v80, v81, 0x3e38aa3b, v4
	v_fmamk_f32 v81, v82, 0x3e38aa3b, v4
	v_fmamk_f32 v82, v83, 0x3e38aa3b, v4
	v_fmamk_f32 v83, v84, 0x3e38aa3b, v4
	v_fmac_f32_e32 v4, 0x3e38aa3b, v85
	v_exp_f32_e32 v90, v90
	v_exp_f32_e32 v85, v4
	v_exp_f32_e32 v91, v91
	v_add_f32_e32 v4, v87, v86
	v_exp_f32_e32 v92, v92
	v_add_f32_e32 v4, v88, v4
	v_exp_f32_e32 v93, v93
	v_add_f32_e32 v4, v89, v4
	v_exp_f32_e32 v94, v94
	v_add_f32_e32 v4, v90, v4
	v_exp_f32_e32 v95, v95
	v_add_f32_e32 v4, v91, v4
	v_exp_f32_e32 v96, v96
	v_add_f32_e32 v4, v92, v4
	v_exp_f32_e32 v97, v97
	v_add_f32_e32 v4, v93, v4
	v_exp_f32_e32 v98, v98
	v_add_f32_e32 v4, v94, v4
	v_exp_f32_e32 v99, v99
	v_add_f32_e32 v4, v95, v4
	v_exp_f32_e32 v100, v100
	v_add_f32_e32 v4, v96, v4
	v_exp_f32_e32 v101, v101
	v_add_f32_e32 v4, v97, v4
	v_exp_f32_e32 v84, v5
	v_add_f32_e32 v4, v98, v4
	v_exp_f32_e32 v70, v70
	v_add_f32_e32 v4, v99, v4
	v_exp_f32_e32 v71, v71
	v_add_f32_e32 v4, v100, v4
	v_exp_f32_e32 v72, v72
	v_add_f32_e32 v4, v101, v4
	v_exp_f32_e32 v73, v73
	v_add_f32_e32 v4, v84, v4
	v_exp_f32_e32 v74, v74
	v_add_f32_e32 v4, v70, v4
	v_exp_f32_e32 v75, v75
	v_add_f32_e32 v4, v71, v4
	v_exp_f32_e32 v76, v76
	v_add_f32_e32 v4, v72, v4
	v_exp_f32_e32 v77, v77
	v_add_f32_e32 v4, v73, v4
	v_exp_f32_e32 v78, v78
	v_add_f32_e32 v4, v74, v4
	v_exp_f32_e32 v79, v79
	v_add_f32_e32 v4, v75, v4
	v_exp_f32_e32 v80, v80
	v_add_f32_e32 v4, v76, v4
	v_exp_f32_e32 v81, v81
	v_add_f32_e32 v4, v77, v4
	v_exp_f32_e32 v82, v82
	v_add_f32_e32 v4, v78, v4
	v_exp_f32_e32 v83, v83
	v_add_f32_e32 v4, v79, v4
	v_add_f32_e32 v4, v80, v4
	v_exp_f32_e32 v122, v122
	v_add_f32_e32 v4, v81, v4
	v_add_f32_e32 v4, v82, v4
	v_add_f32_e32 v4, v83, v4
	v_add_f32_e32 v4, v85, v4
	v_cndmask_b32_e64 v2, v122, 1.0, vcc
	v_mov_b32_e32 v5, v4
	s_nop 1
	v_permlane32_swap_b32_e32 v4, v5
	v_cmp_gt_f32_e32 vcc, 1.0, v2
	v_cvt_pk_bf16_f32 v134, v86, v87
	v_cvt_pk_bf16_f32 v135, v88, v89
	v_cvt_pk_bf16_f32 v136, v90, v91
	v_cvt_pk_bf16_f32 v137, v92, v93
	v_cvt_pk_bf16_f32 v130, v94, v95
	v_cvt_pk_bf16_f32 v131, v96, v97
	v_cvt_pk_bf16_f32 v132, v98, v99
	v_cvt_pk_bf16_f32 v133, v100, v101
	v_cvt_pk_bf16_f32 v126, v84, v70
	v_cvt_pk_bf16_f32 v127, v71, v72
	v_cvt_pk_bf16_f32 v128, v73, v74
	v_cvt_pk_bf16_f32 v129, v75, v76
	v_cvt_pk_bf16_f32 v122, v77, v78
	v_cvt_pk_bf16_f32 v123, v79, v80
	v_cvt_pk_bf16_f32 v124, v81, v82
	v_cvt_pk_bf16_f32 v125, v83, v85
	s_cbranch_vccz .LBB0_704
	s_and_saveexec_b64 s[12:13], s[40:41]
	ds_write_b32 v169, v2 offset:128
	s_or_b64 exec, exec, s[12:13]
	s_waitcnt lgkmcnt(0)
	v_add_u32_e32 v82, s26, v138
	ds_read_b128 v[70:73], v82 offset:224
	ds_read_b128 v[74:77], v82 offset:192
	ds_read_b128 v[78:81], v82 offset:160
	ds_read_b128 v[82:85], v82 offset:128
	s_waitcnt lgkmcnt(0)
	v_pk_mul_f32 v[66:67], v[66:67], v[70:71]
	v_pk_mul_f32 v[62:63], v[62:63], v[74:75]
	v_pk_mul_f32 v[58:59], v[58:59], v[78:79]
	v_pk_mul_f32 v[68:69], v[68:69], v[72:73]
	v_pk_mul_f32 v[64:65], v[64:65], v[76:77]
	v_pk_mul_f32 v[60:61], v[60:61], v[80:81]
	v_pk_mul_f32 v[56:57], v[56:57], v[84:85]
	v_pk_mul_f32 v[54:55], v[54:55], v[82:83]
	v_pk_mul_f32 v[50:51], v[50:51], v[70:71]
	v_pk_mul_f32 v[46:47], v[46:47], v[74:75]
	v_pk_mul_f32 v[42:43], v[42:43], v[78:79]
	v_pk_mul_f32 v[52:53], v[52:53], v[72:73]
	v_pk_mul_f32 v[48:49], v[48:49], v[76:77]
	v_pk_mul_f32 v[44:45], v[44:45], v[80:81]
	v_pk_mul_f32 v[40:41], v[40:41], v[84:85]
	v_pk_mul_f32 v[38:39], v[38:39], v[82:83]
	v_pk_mul_f32 v[34:35], v[34:35], v[70:71]
	v_pk_mul_f32 v[30:31], v[30:31], v[74:75]
	v_pk_mul_f32 v[26:27], v[26:27], v[78:79]
	v_pk_mul_f32 v[36:37], v[36:37], v[72:73]
	v_pk_mul_f32 v[32:33], v[32:33], v[76:77]
	v_pk_mul_f32 v[28:29], v[28:29], v[80:81]
	v_pk_mul_f32 v[24:25], v[24:25], v[84:85]
	v_pk_mul_f32 v[22:23], v[22:23], v[82:83]
	v_pk_mul_f32 v[18:19], v[18:19], v[70:71]
	v_pk_mul_f32 v[14:15], v[14:15], v[74:75]
	v_pk_mul_f32 v[10:11], v[10:11], v[78:79]
	v_pk_mul_f32 v[20:21], v[20:21], v[72:73]
	v_pk_mul_f32 v[16:17], v[16:17], v[76:77]
	v_pk_mul_f32 v[12:13], v[12:13], v[80:81]
	v_pk_mul_f32 v[8:9], v[8:9], v[84:85]
	v_pk_mul_f32 v[6:7], v[6:7], v[82:83]
.LBB0_704:
	s_add_i32 s12, s10, s27
	s_add_i32 s12, s12, 2
	s_cmp_gt_i32 s12, s11
	s_cbranch_scc1 .Lb_nodma
	s_mov_b32 m0, s29
	s_nop 0
	global_load_lds_dwordx4 v140, s[94:95]
	s_mov_b32 m0, s17
	s_nop 0
	global_load_lds_dwordx4 v142, s[100:101]
	s_add_i32 m0, s29, 0x400
	s_nop 0
	global_load_lds_dwordx4 v144, s[94:95]
	s_add_i32 m0, s17, 0x400
	s_nop 0
	global_load_lds_dwordx4 v146, s[100:101]
	s_waitcnt vmcnt(4) lgkmcnt(0)
	s_barrier
